# speedup vs baseline: 1.0025x; 1.0025x over previous
; template <bool MLA> ...
;     ...
;   int kt = nkt - 1;
;   TILE_DMA(kt * 64, 0);
;     ...
;     const int buf = it & 1;
;     asm volatile("s_waitcnt vmcnt(0)" ::: "memory");
;     __syncthreads();
;     if (kt > 0) TILE_DMA((kt - 1) * 64, buf ^ 1);
;     const int k0 = kt * 64;
;     if (k0 < bmax) {
.Lmlp_inactive:
	s_or_b64 exec, exec, s[0:1]
	s_cmpk_ge_u32 s5, 0x100
	s_cbranch_scc1 .LBB0_367
	s_cmp_lt_i32 s93, 1
	s_cbranch_scc1 .LBB0_367
	s_lshl_b32 s0, s39, 14
	s_xor_b32 s0, s0, 0x4000
	v_add_u32_e32 v66, s94, v222
	v_ashrrev_i32_e32 v67, 31, v66
	v_add_u32_e32 v68, s0, v209
	v_lshlrev_b64 v[66:67], 11, v[66:67]
	v_readfirstlane_b32 s0, v68
	v_lshl_add_u64 v[66:67], v[148:149], 0, v[66:67]
	s_mov_b32 m0, s0
	v_add_u32_e32 v68, 0x2000, v68
	global_load_lds_dwordx4 v[66:67], off
	v_add_u32_e32 v66, s94, v221
	v_ashrrev_i32_e32 v67, 31, v66
	v_readfirstlane_b32 s0, v68
	v_lshlrev_b64 v[66:67], 11, v[66:67]
	s_mov_b32 m0, s0
	s_xor_b32 s0, s39, 1
	v_lshl_add_u64 v[66:67], v[148:149], 0, v[66:67]
	s_mulk_i32 s0, 0x6000
	global_load_lds_dwordx4 v[66:67], off
	v_add_u32_e32 v66, s94, v220
	v_add_u32_e32 v68, s0, v209
	v_ashrrev_i32_e32 v67, 31, v66
	v_add_u32_e32 v69, 0x8000, v68
	v_lshlrev_b64 v[66:67], v152, v[66:67]
	v_readfirstlane_b32 s0, v69
	v_lshl_add_u64 v[66:67], v[154:155], 0, v[66:67]
	s_mov_b32 m0, s0
	v_add_u32_e32 v69, 0xa000, v68
	global_load_lds_dwordx4 v[66:67], off
	v_add_u32_e32 v66, s94, v219
	v_ashrrev_i32_e32 v67, 31, v66
	v_lshlrev_b64 v[66:67], v156, v[66:67]
	v_readfirstlane_b32 s0, v69
	v_lshl_add_u64 v[66:67], v[158:159], 0, v[66:67]
	s_mov_b32 m0, s0
	v_add_u32_e32 v68, 0xc000, v68
	global_load_lds_dwordx4 v[66:67], off
	v_add_u32_e32 v66, s94, v218
	v_ashrrev_i32_e32 v67, 31, v66
	v_lshlrev_b64 v[66:67], v150, v[66:67]
	v_readfirstlane_b32 s0, v68
	v_lshl_add_u64 v[66:67], v[160:161], 0, v[66:67]
	s_mov_b32 m0, s0
	s_nop 0
	global_load_lds_dwordx4 v[66:67], off
	s_branch .LBB0_367

; template <bool MLA> ...
;     ...
;   int kt = nkt - 1;
;   TILE_DMA(kt * 64, 0);
;     ...
;     const int buf = it & 1;
;     asm volatile("s_waitcnt vmcnt(0)" ::: "memory");
;     __syncthreads();
;     if (kt > 0) TILE_DMA((kt - 1) * 64, buf ^ 1);
;     const int k0 = kt * 64;
;     if (k0 < bmax) {
;       const char* Ks = K_lds + buf * SHM_K + r32 * KP;
;       f32x16 p0, p1;
; #pragma unroll
;       for (int r = 0; r < 16; ++r) { p0[r] = 0.f; p1[r] = 0.f; }
; #pragma unroll
;       for (int d0 = 0; d0 < ND0; ++d0) { const int off = kq4[d0 & 3] + (d0 >> 2) * 128;
;         bf16x8 b0 = *reinterpret_cast<const bf16x8*>(Ks + off);
;         bf16x8 b1 = *reinterpret_cast<const bf16x8*>(Ks + off + 32 * KP);
;         p0 = __builtin_amdgcn_mfma_f32_32x32x16_bf16(b0, qr[d0], p0, 0, 0, 0);
;         p1 = __builtin_amdgcn_mfma_f32_32x32x16_bf16(b1, qr[d0], p1, 0, 0, 0); }
.LBB0_368:
	s_waitcnt vmcnt(0)
	s_and_b32 s39, s38, 1
	s_cmp_lt_i32 s93, 1
	s_waitcnt lgkmcnt(0)
	s_barrier
	s_cmpk_lt_u32 s5, 0x100
	s_cbranch_scc1 .Lmlp_hdr_done
	s_cmp_lt_i32 s93, 1
	s_cbranch_scc1 .Lmlp_hdr_done
	s_lshl_b32 s0, s39, 14
	s_xor_b32 s0, s0, 0x4000
	v_add_u32_e32 v66, s94, v222
	v_ashrrev_i32_e32 v67, 31, v66
	v_add_u32_e32 v68, s0, v209
	v_lshlrev_b64 v[66:67], 11, v[66:67]
	v_readfirstlane_b32 s0, v68
	v_lshl_add_u64 v[66:67], v[148:149], 0, v[66:67]
	s_mov_b32 m0, s0
	v_add_u32_e32 v68, 0x2000, v68
	global_load_lds_dwordx4 v[66:67], off
	v_add_u32_e32 v66, s94, v221
	v_ashrrev_i32_e32 v67, 31, v66
	v_readfirstlane_b32 s0, v68
	v_lshlrev_b64 v[66:67], 11, v[66:67]
	s_mov_b32 m0, s0
	s_xor_b32 s0, s39, 1
	v_lshl_add_u64 v[66:67], v[148:149], 0, v[66:67]
	s_mulk_i32 s0, 0x6000
	global_load_lds_dwordx4 v[66:67], off
	v_add_u32_e32 v66, s94, v220
	v_add_u32_e32 v68, s0, v209
	v_ashrrev_i32_e32 v67, 31, v66
	v_add_u32_e32 v69, 0x8000, v68
	v_lshlrev_b64 v[66:67], v152, v[66:67]
	v_readfirstlane_b32 s0, v69
	v_lshl_add_u64 v[66:67], v[154:155], 0, v[66:67]
	s_mov_b32 m0, s0
	v_add_u32_e32 v69, 0xa000, v68
	global_load_lds_dwordx4 v[66:67], off
	v_add_u32_e32 v66, s94, v219
	v_ashrrev_i32_e32 v67, 31, v66
	v_lshlrev_b64 v[66:67], v156, v[66:67]
	v_readfirstlane_b32 s0, v69
	v_lshl_add_u64 v[66:67], v[158:159], 0, v[66:67]
	s_mov_b32 m0, s0
	v_add_u32_e32 v68, 0xc000, v68
	global_load_lds_dwordx4 v[66:67], off
	v_add_u32_e32 v66, s94, v218
	v_ashrrev_i32_e32 v67, 31, v66
	v_lshlrev_b64 v[66:67], v150, v[66:67]
	v_readfirstlane_b32 s0, v68
	v_lshl_add_u64 v[66:67], v[160:161], 0, v[66:67]
	s_mov_b32 m0, s0
	s_nop 0
	global_load_lds_dwordx4 v[66:67], off
.Lmlp_hdr_done:
.LBB0_370:
	s_add_i32 s12, s72, s94
	s_addk_i32 s12, 0xc0
	v_cmp_lt_i32_e32 vcc, s12, v215
	s_and_saveexec_b64 s[0:1], vcc
	s_cbranch_execz .Lmlp_inactive
	s_mul_i32 s13, s39, 0x6000
	v_add_u32_e32 v223, s13, v216
	v_add_u32_e32 v228, v223, v213
	v_add_u32_e32 v229, v223, v212
	v_add_u32_e32 v230, v223, v211
	v_add_u32_e32 v223, v223, v210
	ds_read_b128 v[224:227], v228 offset:32768
	ds_read_b128 v[232:235], v229 offset:32768
	ds_read_b128 v[236:239], v228 offset:45056
	ds_read_b128 v[240:243], v229 offset:45056
	v_cmp_ge_i32_e32 vcc, s12, v214
	s_waitcnt lgkmcnt(3)
	v_mfma_f32_32x32x16_bf16 v[66:81], v[224:227], v[142:145], 0
	ds_read_b128 v[224:227], v230 offset:32768
	s_waitcnt lgkmcnt(3)
	v_mfma_f32_32x32x16_bf16 v[66:81], v[232:235], v[138:141], v[66:81]
	ds_read_b128 v[232:235], v230 offset:45056
	s_waitcnt lgkmcnt(3)
	v_mfma_f32_32x32x16_bf16 v[82:97], v[236:239], v[142:145], 0
	ds_read_b128 v[236:239], v223 offset:32768
	s_waitcnt lgkmcnt(3)
	v_mfma_f32_32x32x16_bf16 v[82:97], v[240:243], v[138:141], v[82:97]
	ds_read_b128 v[240:243], v223 offset:45056
	s_waitcnt lgkmcnt(3)
	v_mfma_f32_32x32x16_bf16 v[66:81], v[224:227], v[134:137], v[66:81]
	ds_read_b128 v[224:227], v228 offset:32896
	s_waitcnt lgkmcnt(3)
	v_mfma_f32_32x32x16_bf16 v[82:97], v[232:235], v[134:137], v[82:97]
	ds_read_b128 v[232:235], v228 offset:45184
	s_waitcnt lgkmcnt(3)
	v_mfma_f32_32x32x16_bf16 v[66:81], v[236:239], v[130:133], v[66:81]
	ds_read_b128 v[236:239], v229 offset:32896
	s_waitcnt lgkmcnt(3)
	v_mfma_f32_32x32x16_bf16 v[82:97], v[240:243], v[130:133], v[82:97]
	ds_read_b128 v[240:243], v229 offset:45184
	s_waitcnt lgkmcnt(3)
	v_mfma_f32_32x32x16_bf16 v[66:81], v[224:227], v[126:129], v[66:81]
	ds_read_b128 v[224:227], v230 offset:32896
	s_waitcnt lgkmcnt(3)
	v_mfma_f32_32x32x16_bf16 v[82:97], v[232:235], v[126:129], v[82:97]
	ds_read_b128 v[232:235], v230 offset:45184
	s_waitcnt lgkmcnt(3)
	v_mfma_f32_32x32x16_bf16 v[66:81], v[236:239], v[122:125], v[66:81]
	ds_read_b128 v[236:239], v223 offset:32896
	s_waitcnt lgkmcnt(3)
	v_mfma_f32_32x32x16_bf16 v[82:97], v[240:243], v[122:125], v[82:97]
	ds_read_b128 v[240:243], v223 offset:45184
	s_waitcnt lgkmcnt(3)
	v_mfma_f32_32x32x16_bf16 v[66:81], v[224:227], v[118:121], v[66:81]
	ds_read_b128 v[224:227], v228 offset:33024
	s_waitcnt lgkmcnt(3)
	v_mfma_f32_32x32x16_bf16 v[82:97], v[232:235], v[118:121], v[82:97]
	ds_read_b128 v[232:235], v228 offset:45312
	s_waitcnt lgkmcnt(3)
	v_mfma_f32_32x32x16_bf16 v[66:81], v[236:239], v[114:117], v[66:81]
	ds_read_b128 v[236:239], v229 offset:33024
	s_waitcnt lgkmcnt(3)
	v_mfma_f32_32x32x16_bf16 v[82:97], v[240:243], v[114:117], v[82:97]
	ds_read_b128 v[240:243], v229 offset:45312
	s_waitcnt lgkmcnt(3)
	v_mfma_f32_32x32x16_bf16 v[66:81], v[224:227], v[110:113], v[66:81]
	ds_read_b128 v[224:227], v230 offset:33024
	s_waitcnt lgkmcnt(3)
	v_mfma_f32_32x32x16_bf16 v[82:97], v[232:235], v[110:113], v[82:97]
	ds_read_b128 v[232:235], v230 offset:45312
	s_waitcnt lgkmcnt(3)
	v_mfma_f32_32x32x16_bf16 v[66:81], v[236:239], v[106:109], v[66:81]
	ds_read_b128 v[236:239], v223 offset:33024
	s_waitcnt lgkmcnt(3)
	v_mfma_f32_32x32x16_bf16 v[82:97], v[240:243], v[106:109], v[82:97]
	ds_read_b128 v[240:243], v223 offset:45312
	s_waitcnt lgkmcnt(3)
	v_mfma_f32_32x32x16_bf16 v[66:81], v[224:227], v[102:105], v[66:81]
	s_waitcnt lgkmcnt(2)
	v_mfma_f32_32x32x16_bf16 v[82:97], v[232:235], v[102:105], v[82:97]
	s_waitcnt lgkmcnt(1)
	v_mfma_f32_32x32x16_bf16 v[66:81], v[236:239], v[98:101], v[66:81]
	s_waitcnt lgkmcnt(0)
	v_mfma_f32_32x32x16_bf16 v[82:97], v[240:243], v[98:101], v[82:97]
	s_cmpk_ge_u32 s5, 0x100
	s_cbranch_scc1 .Lmlp_nodma
	s_cmp_lt_i32 s93, 1
	s_cbranch_scc1 .Lmlp_nodma
	s_lshl_b32 s13, s39, 14
	s_xor_b32 s13, s13, 0x4000
	v_add_u32_e32 v244, s94, v222
	v_ashrrev_i32_e32 v245, 31, v244
	v_add_u32_e32 v246, s13, v209
	v_lshlrev_b64 v[244:245], 11, v[244:245]
	v_readfirstlane_b32 s13, v246
	v_lshl_add_u64 v[244:245], v[148:149], 0, v[244:245]
	s_mov_b32 m0, s13
	v_add_u32_e32 v246, 0x2000, v246
	global_load_lds_dwordx4 v[244:245], off
	v_add_u32_e32 v244, s94, v221
	v_ashrrev_i32_e32 v245, 31, v244
	v_readfirstlane_b32 s13, v246
	v_lshlrev_b64 v[244:245], 11, v[244:245]
	s_mov_b32 m0, s13
	s_xor_b32 s13, s39, 1
	v_lshl_add_u64 v[244:245], v[148:149], 0, v[244:245]
	s_mulk_i32 s13, 0x6000
	global_load_lds_dwordx4 v[244:245], off
	v_add_u32_e32 v244, s94, v220
	v_add_u32_e32 v246, s13, v209
	v_ashrrev_i32_e32 v245, 31, v244
	v_add_u32_e32 v247, 0x8000, v246
	v_lshlrev_b64 v[244:245], v152, v[244:245]
	v_readfirstlane_b32 s13, v247
	v_lshl_add_u64 v[244:245], v[154:155], 0, v[244:245]
	s_mov_b32 m0, s13
	v_add_u32_e32 v247, 0xa000, v246
	global_load_lds_dwordx4 v[244:245], off
	v_add_u32_e32 v244, s94, v219
	v_ashrrev_i32_e32 v245, 31, v244
	v_lshlrev_b64 v[244:245], v156, v[244:245]
	v_readfirstlane_b32 s13, v247
	v_lshl_add_u64 v[244:245], v[158:159], 0, v[244:245]
	s_mov_b32 m0, s13
	v_add_u32_e32 v246, 0xc000, v246
	global_load_lds_dwordx4 v[244:245], off
	v_add_u32_e32 v244, s94, v218
	v_ashrrev_i32_e32 v245, 31, v244
	v_lshlrev_b64 v[244:245], v150, v[244:245]
	v_readfirstlane_b32 s13, v246
	v_lshl_add_u64 v[244:245], v[160:161], 0, v[244:245]
	s_mov_b32 m0, s13
	s_nop 0
	global_load_lds_dwordx4 v[244:245], off

; template <bool MLA> ...
;     ...
;   int kt = nkt - 1;
;   TILE_DMA(kt * 64, 0);
;     ...
;     const int buf = it & 1;
;     asm volatile("s_waitcnt vmcnt(0)" ::: "memory");
;     __syncthreads();
;     if (kt > 0) TILE_DMA((kt - 1) * 64, buf ^ 1);
;     const int k0 = kt * 64;
;     if (k0 < bmax) {
.Lsbp_inactive:
	s_or_b64 exec, exec, s[8:9]
	s_cmpk_ge_u32 s5, 0x100
	s_cbranch_scc1 .LBB0_427
	s_cmp_lt_i32 s39, 1
	s_cbranch_scc1 .LBB0_427
	s_lshl_b32 s0, s13, 14
	s_xor_b32 s0, s0, 0x4000
	v_add_u32_e32 v34, s68, v172
	v_ashrrev_i32_e32 v35, 31, v34
	v_add_u32_e32 v32, s0, v156
	v_lshlrev_b64 v[34:35], 11, v[34:35]
	v_readfirstlane_b32 s0, v32
	v_lshl_add_u64 v[34:35], v[144:145], 0, v[34:35]
	s_mov_b32 m0, s0
	v_add_u32_e32 v36, 0x2000, v32
	global_load_lds_dwordx4 v[34:35], off
	v_add_u32_e32 v34, s68, v171
	v_ashrrev_i32_e32 v35, 31, v34
	v_lshlrev_b64 v[34:35], 11, v[34:35]
	v_readfirstlane_b32 s0, v36
	v_lshl_add_u64 v[34:35], v[144:145], 0, v[34:35]
	s_mov_b32 m0, s0
	v_add_u32_e32 v36, 0x8000, v32
	global_load_lds_dwordx4 v[34:35], off
	v_add_u32_e32 v34, s68, v170
	v_ashrrev_i32_e32 v35, 31, v34
	v_lshlrev_b64 v[34:35], 11, v[34:35]
	v_readfirstlane_b32 s0, v36
	v_lshl_add_u64 v[34:35], v[150:151], 0, v[34:35]
	s_mov_b32 m0, s0
	v_add_u32_e32 v32, 0xa000, v32
	global_load_lds_dwordx4 v[34:35], off
	v_add_u32_e32 v34, s68, v169
	v_ashrrev_i32_e32 v35, 31, v34
	v_lshlrev_b64 v[34:35], 11, v[34:35]
	v_readfirstlane_b32 s0, v32
	v_lshl_add_u64 v[34:35], v[152:153], 0, v[34:35]
	s_mov_b32 m0, s0
	s_nop 0
	global_load_lds_dwordx4 v[34:35], off
	s_branch .LBB0_427

; template <bool MLA> ...
;     ...
;   int kt = nkt - 1;
;   TILE_DMA(kt * 64, 0);
;     ...
;     const int buf = it & 1;
;     asm volatile("s_waitcnt vmcnt(0)" ::: "memory");
;     __syncthreads();
;     if (kt > 0) TILE_DMA((kt - 1) * 64, buf ^ 1);
;     const int k0 = kt * 64;
;     if (k0 < bmax) {
;       const char* Ks = K_lds + buf * SHM_K + r32 * KP;
;       f32x16 p0, p1;
; #pragma unroll
;       for (int r = 0; r < 16; ++r) { p0[r] = 0.f; p1[r] = 0.f; }
; #pragma unroll
;       for (int d0 = 0; d0 < ND0; ++d0) { const int off = kq4[d0 & 3] + (d0 >> 2) * 128;
;         bf16x8 b0 = *reinterpret_cast<const bf16x8*>(Ks + off);
;         bf16x8 b1 = *reinterpret_cast<const bf16x8*>(Ks + off + 32 * KP);
;         p0 = __builtin_amdgcn_mfma_f32_32x32x16_bf16(b0, qr[d0], p0, 0, 0, 0);
;         p1 = __builtin_amdgcn_mfma_f32_32x32x16_bf16(b1, qr[d0], p1, 0, 0, 0); }
.LBB0_428:
	s_waitcnt vmcnt(0)
	s_and_b32 s13, s69, 1
	s_cmp_lt_i32 s39, 1
	s_waitcnt lgkmcnt(0)
	s_barrier
	s_cmpk_lt_u32 s5, 0x100
	s_cbranch_scc1 .Lsbp_hdr_done
	s_cmp_lt_i32 s39, 1
	s_cbranch_scc1 .Lsbp_hdr_done
	s_lshl_b32 s0, s13, 14
	s_xor_b32 s0, s0, 0x4000
	v_add_u32_e32 v34, s68, v172
	v_ashrrev_i32_e32 v35, 31, v34
	v_add_u32_e32 v32, s0, v156
	v_lshlrev_b64 v[34:35], 11, v[34:35]
	v_readfirstlane_b32 s0, v32
	v_lshl_add_u64 v[34:35], v[144:145], 0, v[34:35]
	s_mov_b32 m0, s0
	v_add_u32_e32 v36, 0x2000, v32
	global_load_lds_dwordx4 v[34:35], off
	v_add_u32_e32 v34, s68, v171
	v_ashrrev_i32_e32 v35, 31, v34
	v_lshlrev_b64 v[34:35], 11, v[34:35]
	v_readfirstlane_b32 s0, v36
	v_lshl_add_u64 v[34:35], v[144:145], 0, v[34:35]
	s_mov_b32 m0, s0
	v_add_u32_e32 v36, 0x8000, v32
	global_load_lds_dwordx4 v[34:35], off
	v_add_u32_e32 v34, s68, v170
	v_ashrrev_i32_e32 v35, 31, v34
	v_lshlrev_b64 v[34:35], 11, v[34:35]
	v_readfirstlane_b32 s0, v36
	v_lshl_add_u64 v[34:35], v[150:151], 0, v[34:35]
	s_mov_b32 m0, s0
	v_add_u32_e32 v32, 0xa000, v32
	global_load_lds_dwordx4 v[34:35], off
	v_add_u32_e32 v34, s68, v169
	v_ashrrev_i32_e32 v35, 31, v34
	v_lshlrev_b64 v[34:35], 11, v[34:35]
	v_readfirstlane_b32 s0, v32
	v_lshl_add_u64 v[34:35], v[152:153], 0, v[34:35]
	s_mov_b32 m0, s0
	s_nop 0
	global_load_lds_dwordx4 v[34:35], off
.Lsbp_hdr_done:
.LBB0_430:
	s_add_i32 s12, s72, s68
	s_add_i32 s0, s12, 0xc0
	v_cmp_lt_i32_e64 s[0:1], s0, v161
	s_and_saveexec_b64 s[8:9], s[0:1]
	s_cbranch_execz .Lsbp_inactive
	s_lshl_b32 s73, s13, 14
	v_add_u32_e32 v32, s73, v166
	v_add_u32_e32 v42, v32, v162
	v_add_u32_e32 v43, v32, v163
	v_add_u32_e32 v44, v32, v164
	v_add_u32_e32 v32, v32, v165
	ds_read_b128 v[34:37], v42 offset:32768
	ds_read_b128 v[38:41], v42 offset:40960
	ds_read_b128 v[216:219], v43 offset:32768
	ds_read_b128 v[220:223], v43 offset:40960
	ds_read_b128 v[224:227], v44 offset:32768
	ds_read_b128 v[228:231], v44 offset:40960
	s_addk_i32 s12, 0x100
	v_cmp_le_i32_e64 s[0:1], s12, v160
	s_waitcnt lgkmcnt(5)
	v_mfma_f32_32x32x16_bf16 v[80:95], v[34:37], v[112:115], 0
	ds_read_b128 v[34:37], v32 offset:32768
	s_waitcnt lgkmcnt(5)
	v_mfma_f32_32x32x16_bf16 v[96:111], v[38:41], v[112:115], 0
	ds_read_b128 v[38:41], v32 offset:40960
	s_waitcnt lgkmcnt(5)
	v_mfma_f32_32x32x16_bf16 v[80:95], v[216:219], v[116:119], v[80:95]
	ds_read_b128 v[216:219], v42 offset:32896
	s_waitcnt lgkmcnt(5)
	v_mfma_f32_32x32x16_bf16 v[96:111], v[220:223], v[116:119], v[96:111]
	ds_read_b128 v[220:223], v42 offset:41088
	s_waitcnt lgkmcnt(5)
	v_mfma_f32_32x32x16_bf16 v[80:95], v[224:227], v[120:123], v[80:95]
	ds_read_b128 v[224:227], v43 offset:32896
	s_waitcnt lgkmcnt(5)
	v_mfma_f32_32x32x16_bf16 v[96:111], v[228:231], v[120:123], v[96:111]
	ds_read_b128 v[228:231], v43 offset:41088
	s_waitcnt lgkmcnt(5)
	v_mfma_f32_32x32x16_bf16 v[80:95], v[34:37], v[124:127], v[80:95]
	ds_read_b128 v[34:37], v44 offset:32896
	s_waitcnt lgkmcnt(5)
	v_mfma_f32_32x32x16_bf16 v[96:111], v[38:41], v[124:127], v[96:111]
	ds_read_b128 v[38:41], v44 offset:41088
	s_waitcnt lgkmcnt(5)
	v_mfma_f32_32x32x16_bf16 v[80:95], v[216:219], v[128:131], v[80:95]
	ds_read_b128 v[216:219], v32 offset:32896
	s_waitcnt lgkmcnt(5)
	v_mfma_f32_32x32x16_bf16 v[96:111], v[220:223], v[128:131], v[96:111]
	ds_read_b128 v[220:223], v32 offset:41088
	s_waitcnt lgkmcnt(5)
	v_mfma_f32_32x32x16_bf16 v[80:95], v[224:227], v[132:135], v[80:95]
	s_waitcnt lgkmcnt(4)
	v_mfma_f32_32x32x16_bf16 v[96:111], v[228:231], v[132:135], v[96:111]
	s_waitcnt lgkmcnt(3)
	v_mfma_f32_32x32x16_bf16 v[80:95], v[34:37], v[136:139], v[80:95]
	s_waitcnt lgkmcnt(2)
	v_mfma_f32_32x32x16_bf16 v[96:111], v[38:41], v[136:139], v[96:111]
	s_waitcnt lgkmcnt(1)
	v_mfma_f32_32x32x16_bf16 v[80:95], v[216:219], v[140:143], v[80:95]
	s_waitcnt lgkmcnt(0)
	v_mfma_f32_32x32x16_bf16 v[96:111], v[220:223], v[140:143], v[96:111]
	s_cmpk_ge_u32 s5, 0x100
	s_cbranch_scc1 .Lsbp_nodma
	s_cmp_lt_i32 s39, 1
	s_cbranch_scc1 .Lsbp_nodma
	s_lshl_b32 s12, s13, 14
	s_xor_b32 s12, s12, 0x4000
	v_add_u32_e32 v234, s68, v172
	v_ashrrev_i32_e32 v235, 31, v234
	v_add_u32_e32 v232, s12, v156
	v_lshlrev_b64 v[234:235], 11, v[234:235]
	v_readfirstlane_b32 s12, v232
	v_lshl_add_u64 v[234:235], v[144:145], 0, v[234:235]
	s_mov_b32 m0, s12
	v_add_u32_e32 v236, 0x2000, v232
	global_load_lds_dwordx4 v[234:235], off
	v_add_u32_e32 v234, s68, v171
	v_ashrrev_i32_e32 v235, 31, v234
	v_lshlrev_b64 v[234:235], 11, v[234:235]
	v_readfirstlane_b32 s12, v236
	v_lshl_add_u64 v[234:235], v[144:145], 0, v[234:235]
	s_mov_b32 m0, s12
	v_add_u32_e32 v236, 0x8000, v232
	global_load_lds_dwordx4 v[234:235], off
	v_add_u32_e32 v234, s68, v170
	v_ashrrev_i32_e32 v235, 31, v234
	v_lshlrev_b64 v[234:235], 11, v[234:235]
	v_readfirstlane_b32 s12, v236
	v_lshl_add_u64 v[234:235], v[150:151], 0, v[234:235]
	s_mov_b32 m0, s12
	v_add_u32_e32 v232, 0xa000, v232
	global_load_lds_dwordx4 v[234:235], off
	v_add_u32_e32 v234, s68, v169
	v_ashrrev_i32_e32 v235, 31, v234
	v_lshlrev_b64 v[234:235], 11, v[234:235]
	v_readfirstlane_b32 s12, v232
	v_lshl_add_u64 v[234:235], v[152:153], 0, v[234:235]
	s_mov_b32 m0, s12
	s_nop 0
	global_load_lds_dwordx4 v[234:235], off
